# v28 + rw_post token loop: all 46 per-head loads hoisted to iteration top with symbolic address reconstruction, waits recounted
# speedup vs baseline: 1.0260x; 1.0240x over previous
; DEV float bf2f(bf16_t b) { return __uint_as_float(((unsigned)b) << 16); }
; DEV void phase_rw_post(const Params& p) {
;     ...
;   for (int t = gw; t < NTOK; t += nw) {
;     int tb, T;
;     seq_of_token(t, tb, T);
;     const bool hp = t > tb, hn = t < tb + T - 1;
;     const int op = hp ? -RW_LD : 0, on = hn ? RW_LD : 0;
;     const bf16_t* vrow = proj + (size_t)t * RW_LD + 1024 + lane;
;     bf16_t raw[8][6];
;     float bo[8];
; #pragma unroll
;     for (int h = 0; h < 8; ++h) {
;       const size_t o = (size_t)t * 512 + h * 64 + lane;
;       raw[h][0] = yf[o];
;       raw[h][1] = yb[o];
;       raw[h][2] = vrow[h * 64];
;       raw[h][3] = vrow[h * 64 + op];
;       raw[h][4] = vrow[h * 64 + on];
;       raw[h][5] = gate[o];
;       bo[h] = scal[((size_t)t * 8 + h) * 4 + 2];
;     }
;     bf16_t res[8];
; #pragma unroll
;     for (int h = 0; h < 8; ++h) {
;       const int hc = h * 64 + lane;
;       const float y = bf2f(raw[h][0]) + bf2f(raw[h][1]);
;       const float mu = wave_sum_dpp(y) * (1.f / 64.f);
;       const float dy = y - mu;
;       const float var = wave_sum_dpp(dy * dy) * (1.f / 64.f);
;       const float yn = dy * rsqrtf(var + 64e-5f) * p.in[26][hc] + p.in[27][hc];
.LBB0_2394:
	s_movk_i32 s0, 0x4000
	v_cmp_gt_i32_e32 vcc, s0, v138
	v_lshl_add_u64 v[82:83], s[58:59], 0, v[74:75]
	s_mov_b32 s0, 0x1c500000
	v_cndmask_b32_e32 v2, v100, v101, vcc
	v_and_b32_e32 v2, v2, v138
	v_cndmask_b32_e32 v78, v102, v103, vcc
	v_cmp_gt_i32_e64 s[8:9], v138, v2
	v_add_u32_e32 v2, v2, v78
	v_cmp_lt_i32_e32 vcc, v138, v2
	v_cndmask_b32_e64 v79, 0, -1, s[8:9]
	v_cndmask_b32_e64 v78, 0, v104, s[8:9]
	v_lshl_add_u64 v[78:79], v[72:73], 0, v[78:79]
	v_cndmask_b32_e32 v2, 0, v105, vcc
	v_lshl_add_u64 v[84:85], s[58:59], 0, v[78:79]
	v_lshl_add_u64 v[78:79], v[72:73], 0, v[2:3]
	v_lshl_add_u64 v[90:91], s[58:59], 0, v[78:79]
	v_add_co_u32_e64 v78, s[10:11], s0, v82
	v_lshl_add_u64 v[88:89], s[58:59], 0, v[76:77]
	s_nop 0
	v_addc_co_u32_e64 v79, s[10:11], 0, v83, s[10:11]
	s_mov_b32 s0, 0x4b00000
	v_add_co_u32_e64 v86, s[10:11], s0, v88
	s_mov_b32 s0, 0x1b00000
	s_nop 0
	v_addc_co_u32_e64 v87, s[10:11], 0, v89, s[10:11]
	global_load_dword v144, v[78:79], off offset:8
	global_load_dword v145, v[78:79], off offset:24
	global_load_dword v146, v[78:79], off offset:40
	global_load_dword v147, v[78:79], off offset:56
	global_load_dword v148, v[78:79], off offset:72
	global_load_dword v149, v[78:79], off offset:88
	global_load_dword v139, v[78:79], off offset:104
	global_load_dword v2, v[78:79], off offset:120
	v_add_co_u32_e64 v78, s[10:11], s0, v88
	global_load_ushort v82, v[86:87], off
	s_nop 0
	v_addc_co_u32_e64 v79, s[10:11], 0, v89, s[10:11]
	global_load_ushort v83, v[78:79], off
	v_lshl_add_u64 v[80:81], s[58:59], 0, v[72:73]
	s_nop 4
	s_mov_b32 s11, 0
	s_mov_b32 s10, 0x7b00000
	v_lshl_add_u64 v[254:255], v[80:81], 0, s[10:11]
	global_load_ushort v156, v[254:255], off offset:2048
	global_load_ushort v157, v[254:255], off offset:2176
	global_load_ushort v158, v[254:255], off offset:2304
	global_load_ushort v159, v[254:255], off offset:2432
	global_load_ushort v160, v[254:255], off offset:2560
	global_load_ushort v161, v[254:255], off offset:2688
	global_load_ushort v162, v[254:255], off offset:2816
	global_load_ushort v163, v[254:255], off offset:2944
	s_mov_b32 s10, 0x7b00000
	v_lshl_add_u64 v[254:255], v[84:85], 0, s[10:11]
	global_load_ushort v164, v[254:255], off offset:2048
	global_load_ushort v165, v[254:255], off offset:2176
	global_load_ushort v166, v[254:255], off offset:2304
	global_load_ushort v167, v[254:255], off offset:2432
	global_load_ushort v168, v[254:255], off offset:2560
	global_load_ushort v169, v[254:255], off offset:2688
	global_load_ushort v170, v[254:255], off offset:2816
	global_load_ushort v171, v[254:255], off offset:2944
	s_mov_b32 s10, 0x7b00000
	v_lshl_add_u64 v[254:255], v[90:91], 0, s[10:11]
	global_load_ushort v172, v[254:255], off offset:2048
	global_load_ushort v173, v[254:255], off offset:2176
	global_load_ushort v174, v[254:255], off offset:2304
	global_load_ushort v175, v[254:255], off offset:2432
	global_load_ushort v193, v[254:255], off offset:2560
	global_load_ushort v195, v[254:255], off offset:2688
	global_load_ushort v196, v[254:255], off offset:2816
	global_load_ushort v197, v[254:255], off offset:2944
	s_mov_b32 s10, 0x18900000
	v_lshl_add_u64 v[254:255], v[88:89], 0, s[10:11]
	global_load_ushort v204, v[254:255], off
	global_load_ushort v205, v[254:255], off offset:128
	global_load_ushort v206, v[254:255], off offset:256
	global_load_ushort v207, v[254:255], off offset:384
	global_load_ushort v208, v[254:255], off offset:512
	global_load_ushort v209, v[254:255], off offset:640
	global_load_ushort v210, v[254:255], off offset:768
	global_load_ushort v211, v[254:255], off offset:896
	s_mov_b32 s10, 0x4b00000
	v_lshl_add_u64 v[254:255], v[88:89], 0, s[10:11]
	global_load_ushort v212, v[254:255], off offset:128
	global_load_ushort v213, v[254:255], off offset:256
	global_load_ushort v227, v[254:255], off offset:384
	global_load_ushort v228, v[254:255], off offset:512
	global_load_ushort v229, v[254:255], off offset:640
	global_load_ushort v230, v[254:255], off offset:768
	global_load_ushort v231, v[254:255], off offset:896
	s_mov_b32 s10, 0x1b00000
	v_lshl_add_u64 v[254:255], v[88:89], 0, s[10:11]
	global_load_ushort v232, v[254:255], off offset:128
	global_load_ushort v233, v[254:255], off offset:256
	global_load_ushort v234, v[254:255], off offset:384
	global_load_ushort v235, v[254:255], off offset:512
	global_load_ushort v236, v[254:255], off offset:640
	global_load_ushort v237, v[254:255], off offset:768
	global_load_ushort v238, v[254:255], off offset:896
	v_add_u32_e32 v138, s14, v138
	v_lshl_add_u64 v[76:77], v[76:77], 0, s[26:27]
	v_lshl_add_u64 v[74:75], v[74:75], 0, s[82:83]
	v_lshl_add_u64 v[72:73], v[72:73], 0, s[34:35]
	s_waitcnt vmcnt(47)
	v_lshlrev_b32_e32 v82, 16, v82
	s_waitcnt vmcnt(46)
	v_lshlrev_b32_e32 v83, 16, v83
	v_add_f32_e32 v150, v82, v83
	s_nop 1
	v_add_f32_dpp v82, v150, v150 row_ror:8 row_mask:0xf bank_mask:0xf bound_ctrl:1
	s_nop 1
	v_add_f32_dpp v82, v82, v82 row_ror:4 row_mask:0xf bank_mask:0xf bound_ctrl:1
	s_nop 1
	v_add_f32_dpp v82, v82, v82 row_ror:2 row_mask:0xf bank_mask:0xf bound_ctrl:1
	s_nop 1
	v_add_f32_dpp v82, v82, v82 row_ror:1 row_mask:0xf bank_mask:0xf bound_ctrl:1
	s_nop 0
	v_readlane_b32 s10, v82, 16
	v_readlane_b32 s11, v82, 48
	v_readlane_b32 s0, v82, 0
	v_readlane_b32 s1, v82, 32
	v_mov_b32_e32 v82, s10
	v_mov_b32_e32 v83, s11
	v_pk_add_f32 v[82:83], s[0:1], v[82:83]
	s_nop 0
	v_add_f32_e32 v82, v82, v83
	v_fmac_f32_e32 v150, 0xbc800000, v82
	v_mul_f32_e32 v82, v150, v150
	s_nop 1
	v_mov_b32_dpp v82, v82 row_ror:8 row_mask:0xf bank_mask:0xf bound_ctrl:1
	v_fmac_f32_e32 v82, v150, v150
	s_nop 1
	v_add_f32_dpp v82, v82, v82 row_ror:4 row_mask:0xf bank_mask:0xf bound_ctrl:1
	s_nop 1
	v_add_f32_dpp v82, v82, v82 row_ror:2 row_mask:0xf bank_mask:0xf bound_ctrl:1
	s_nop 1
	v_add_f32_dpp v82, v82, v82 row_ror:1 row_mask:0xf bank_mask:0xf bound_ctrl:1
	s_nop 0
	v_readlane_b32 s10, v82, 16
	v_readlane_b32 s11, v82, 48
	v_readlane_b32 s0, v82, 0
	v_readlane_b32 s1, v82, 32
	v_mov_b32_e32 v82, s10
	v_mov_b32_e32 v83, s11
	v_add_co_u32_e64 v80, s[10:11], s92, v80
	v_pk_add_f32 v[140:141], s[0:1], v[82:83]
	s_nop 0
	v_addc_co_u32_e64 v81, s[10:11], 0, v81, s[10:11]
	s_waitcnt vmcnt(45)
; DEV float bf2f(bf16_t b) { return __uint_as_float(((unsigned)b) << 16); }
; DEV void phase_rw_post(const Params& p) {
;     ...
;     for (int h = 0; h < 8; ++h) {
;       const int hc = h * 64 + lane;
;       const float y = bf2f(raw[h][0]) + bf2f(raw[h][1]);
;       const float mu = wave_sum_dpp(y) * (1.f / 64.f);
;       const float dy = y - mu;
;       const float var = wave_sum_dpp(dy * dy) * (1.f / 64.f);
;       const float yn = dy * rsqrtf(var + 64e-5f) * p.in[26][hc] + p.in[27][hc];
;       const float x = bf2f(raw[h][2]);
;       const float v = x + p.in[14][1024 + hc] * ((hp ? bf2f(raw[h][3]) : 0.f) - x) + p.in[15][1024 + hc] * ((hn ? bf2f(raw[h][4]) : 0.f) - x);
;       res[h] = f2bf((yn + bo[h] * v) * bf2f(raw[h][5]));
	v_mov_b32_e32 v82, v156
	s_mov_b32 s0, 0x18900000
	v_mov_b32_e32 v143, v140
	v_lshlrev_b32_e32 v151, 16, v82
	v_add_co_u32_e64 v82, s[10:11], s92, v84
	s_nop 1
	v_addc_co_u32_e64 v83, s[10:11], 0, v85, s[10:11]
	s_waitcnt vmcnt(37)
	v_mov_b32_e32 v84, v164
	v_lshlrev_b32_e32 v84, 16, v84
	v_cndmask_b32_e64 v84, 0, v84, s[8:9]
	v_sub_f32_e32 v142, v84, v151
	v_add_co_u32_e64 v84, s[10:11], s92, v90
	s_nop 1
	v_addc_co_u32_e64 v85, s[10:11], 0, v91, s[10:11]
	s_waitcnt vmcnt(29)
	v_mov_b32_e32 v90, v172
	v_add_co_u32_e64 v88, s[10:11], s0, v88
	v_lshlrev_b32_e32 v90, 16, v90
	v_cndmask_b32_e32 v90, 0, v90, vcc
	v_sub_f32_e32 v90, v90, v151
	v_fmac_f32_e32 v151, v106, v142
	v_addc_co_u32_e64 v89, s[10:11], 0, v89, s[10:11]
	v_fmac_f32_e32 v151, v107, v90
	s_waitcnt vmcnt(21)
	v_mov_b32_e32 v90, v204
	v_lshlrev_b32_e32 v152, 16, v90
	s_waitcnt vmcnt(13)
	v_mov_b32_e32 v90, v212
	s_waitcnt vmcnt(6)
	v_mov_b32_e32 v91, v232
	v_lshlrev_b32_e32 v90, 16, v90
	v_lshlrev_b32_e32 v91, 16, v91
	v_add_f32_e32 v153, v90, v91
	s_nop 1
	v_add_f32_dpp v90, v153, v153 row_ror:8 row_mask:0xf bank_mask:0xf bound_ctrl:1
	s_nop 1
	v_add_f32_dpp v90, v90, v90 row_ror:4 row_mask:0xf bank_mask:0xf bound_ctrl:1
	s_nop 1
	v_add_f32_dpp v90, v90, v90 row_ror:2 row_mask:0xf bank_mask:0xf bound_ctrl:1
	s_nop 1
	v_add_f32_dpp v90, v90, v90 row_ror:1 row_mask:0xf bank_mask:0xf bound_ctrl:1
	s_nop 0
	v_readlane_b32 s10, v90, 16
	v_readlane_b32 s11, v90, 48
	v_readlane_b32 s0, v90, 0
	v_readlane_b32 s1, v90, 32
	v_mov_b32_e32 v90, s10
	v_mov_b32_e32 v91, s11
	v_pk_add_f32 v[90:91], s[0:1], v[90:91]
	s_nop 0
	v_add_f32_e32 v90, v90, v91
	v_fmac_f32_e32 v153, 0xbc800000, v90
	v_mul_f32_e32 v90, v153, v153
	s_nop 1
	v_mov_b32_dpp v90, v90 row_ror:8 row_mask:0xf bank_mask:0xf bound_ctrl:1
	v_fmac_f32_e32 v90, v153, v153
	s_nop 1
	v_add_f32_dpp v90, v90, v90 row_ror:4 row_mask:0xf bank_mask:0xf bound_ctrl:1
	s_nop 1
	v_add_f32_dpp v90, v90, v90 row_ror:2 row_mask:0xf bank_mask:0xf bound_ctrl:1
	s_nop 1
	v_add_f32_dpp v90, v90, v90 row_ror:1 row_mask:0xf bank_mask:0xf bound_ctrl:1
	s_nop 0
	v_readlane_b32 s10, v90, 16
	v_readlane_b32 s11, v90, 48
	v_readlane_b32 s0, v90, 0
	v_readlane_b32 s1, v90, 32
	v_mov_b32_e32 v90, s10
	v_mov_b32_e32 v91, s11
	v_pk_add_f32 v[90:91], s[0:1], v[90:91]
	s_mov_b32 s0, 0x3a27c5ac
	v_mov_b32_e32 v142, v90
	v_mov_b32_e32 v140, v91
	v_pk_add_f32 v[140:141], v[142:143], v[140:141]
	v_mov_b64_e32 v[90:91], s[0:1]
	v_pk_fma_f32 v[140:141], v[140:141], s[6:7], v[90:91] op_sel_hi:[1,0,0]
	v_mov_b32_e32 v143, v173
	v_mul_f32_e32 v142, 0x4b800000, v141
	v_cmp_gt_f32_e64 s[12:13], s93, v141
	v_cmp_gt_f32_e64 s[10:11], s93, v140
	v_lshlrev_b32_e32 v143, 16, v143
	v_cndmask_b32_e64 v141, v141, v142, s[12:13]
	v_rsq_f32_e32 v141, v141
	v_cndmask_b32_e32 v143, 0, v143, vcc
	v_mul_f32_e32 v142, 0x45800000, v141
	v_cndmask_b32_e64 v141, v141, v142, s[12:13]
	v_mul_f32_e32 v141, v150, v141
	v_fma_f32 v141, v120, v141, v128
	v_fmac_f32_e32 v141, v144, v151
	v_mul_f32_e32 v141, v141, v152
	v_cvt_pk_bf16_f32 v150, v141, s0
	v_mul_f32_e32 v141, 0x4b800000, v140
	v_cndmask_b32_e64 v140, v140, v141, s[10:11]
	v_rsq_f32_e32 v140, v140
	v_mov_b32_e32 v142, v165
	v_mul_f32_e32 v141, 0x45800000, v140
	v_cndmask_b32_e64 v140, v140, v141, s[10:11]
	v_mov_b32_e32 v141, v157
	v_mul_f32_e32 v140, v153, v140
	v_fma_f32 v140, v121, v140, v129
	v_lshlrev_b32_e32 v142, 16, v142
	v_cndmask_b32_e64 v142, 0, v142, s[8:9]
	v_lshlrev_b32_e32 v141, 16, v141
	v_sub_f32_e32 v142, v142, v141
	v_sub_f32_e32 v143, v143, v141
	v_fmac_f32_e32 v141, v108, v142
	v_fmac_f32_e32 v141, v109, v143
	v_fmac_f32_e32 v140, v145, v141
	v_mov_b32_e32 v141, v205
	v_lshlrev_b32_e32 v141, 16, v141
	v_mul_f32_e32 v140, v140, v141
	v_cvt_pk_bf16_f32 v151, v140, s0
	v_mov_b32_e32 v140, v213
	s_waitcnt vmcnt(5)
	v_mov_b32_e32 v141, v233
	v_mov_b32_e32 v142, v158
	v_mov_b32_e32 v143, v174
	v_lshlrev_b32_e32 v140, 16, v140
	v_lshlrev_b32_e32 v141, 16, v141
	v_lshlrev_b32_e32 v153, 16, v142
	v_mov_b32_e32 v142, v166
	v_lshlrev_b32_e32 v143, 16, v143
	v_cndmask_b32_e32 v143, 0, v143, vcc
	v_sub_f32_e32 v143, v143, v153
	v_add_f32_e32 v152, v140, v141
	v_lshlrev_b32_e32 v142, 16, v142
	v_cndmask_b32_e64 v142, 0, v142, s[8:9]
	v_sub_f32_e32 v142, v142, v153
	v_fmac_f32_e32 v153, v110, v142
	v_mov_b32_e32 v142, v206
	v_fmac_f32_e32 v153, v111, v143
	v_add_f32_dpp v140, v152, v152 row_ror:8 row_mask:0xf bank_mask:0xf bound_ctrl:1
	v_lshlrev_b32_e32 v154, 16, v142
	v_mov_b32_e32 v142, v227
	s_waitcnt vmcnt(4)
; DEV float bf2f(bf16_t b) { return __uint_as_float(((unsigned)b) << 16); }
; DEV void phase_rw_post(const Params& p) {
;     ...
;     for (int h = 0; h < 8; ++h) {
;       const int hc = h * 64 + lane;
;       const float y = bf2f(raw[h][0]) + bf2f(raw[h][1]);
;       const float mu = wave_sum_dpp(y) * (1.f / 64.f);
;       const float dy = y - mu;
;       const float var = wave_sum_dpp(dy * dy) * (1.f / 64.f);
;       const float yn = dy * rsqrtf(var + 64e-5f) * p.in[26][hc] + p.in[27][hc];
;       const float x = bf2f(raw[h][2]);
;       const float v = x + p.in[14][1024 + hc] * ((hp ? bf2f(raw[h][3]) : 0.f) - x) + p.in[15][1024 + hc] * ((hn ? bf2f(raw[h][4]) : 0.f) - x);
;       res[h] = f2bf((yn + bo[h] * v) * bf2f(raw[h][5]));
	v_mov_b32_e32 v143, v234
	v_add_f32_dpp v140, v140, v140 row_ror:4 row_mask:0xf bank_mask:0xf bound_ctrl:1
	v_lshlrev_b32_e32 v142, 16, v142
	v_add_f32_dpp v140, v140, v140 row_ror:2 row_mask:0xf bank_mask:0xf bound_ctrl:1
	v_lshlrev_b32_e32 v143, 16, v143
	v_add_f32_e32 v155, v142, v143
	v_add_f32_dpp v140, v140, v140 row_ror:1 row_mask:0xf bank_mask:0xf bound_ctrl:1
	s_nop 0
	v_readlane_b32 s10, v140, 16
	v_readlane_b32 s11, v140, 48
	v_readlane_b32 s0, v140, 0
	v_readlane_b32 s1, v140, 32
	v_mov_b32_e32 v140, s10
	v_mov_b32_e32 v141, s11
	v_pk_add_f32 v[140:141], s[0:1], v[140:141]
	v_add_f32_dpp v142, v155, v155 row_ror:8 row_mask:0xf bank_mask:0xf bound_ctrl:1
	v_add_f32_e32 v140, v140, v141
	v_fmac_f32_e32 v152, 0xbc800000, v140
	v_mul_f32_e32 v140, v152, v152
	v_add_f32_dpp v142, v142, v142 row_ror:4 row_mask:0xf bank_mask:0xf bound_ctrl:1
	s_nop 0
	v_mov_b32_dpp v140, v140 row_ror:8 row_mask:0xf bank_mask:0xf bound_ctrl:1
	v_fmac_f32_e32 v140, v152, v152
	v_add_f32_dpp v142, v142, v142 row_ror:2 row_mask:0xf bank_mask:0xf bound_ctrl:1
	s_nop 0
	v_add_f32_dpp v140, v140, v140 row_ror:4 row_mask:0xf bank_mask:0xf bound_ctrl:1
	v_add_f32_dpp v142, v142, v142 row_ror:1 row_mask:0xf bank_mask:0xf bound_ctrl:1
	s_nop 0
	v_add_f32_dpp v140, v140, v140 row_ror:2 row_mask:0xf bank_mask:0xf bound_ctrl:1
	s_nop 1
	v_add_f32_dpp v140, v140, v140 row_ror:1 row_mask:0xf bank_mask:0xf bound_ctrl:1
	s_nop 0
	v_readlane_b32 s10, v140, 16
	v_readlane_b32 s11, v140, 48
	v_readlane_b32 s0, v140, 0
	v_readlane_b32 s1, v140, 32
	v_mov_b32_e32 v140, s10
	v_mov_b32_e32 v141, s11
	v_readlane_b32 s10, v142, 16
	v_readlane_b32 s11, v142, 48
	v_pk_add_f32 v[140:141], s[0:1], v[140:141]
	v_readlane_b32 s0, v142, 0
	v_readlane_b32 s1, v142, 32
	v_mov_b32_e32 v142, s10
	v_mov_b32_e32 v143, s11
	v_pk_add_f32 v[142:143], s[0:1], v[142:143]
	v_mov_b32_e32 v145, v140
	v_add_f32_e32 v142, v142, v143
	v_fmac_f32_e32 v155, 0xbc800000, v142
	v_mul_f32_e32 v142, v155, v155
	s_nop 1
	v_mov_b32_dpp v142, v142 row_ror:8 row_mask:0xf bank_mask:0xf bound_ctrl:1
	v_fmac_f32_e32 v142, v155, v155
	s_nop 1
	v_add_f32_dpp v142, v142, v142 row_ror:4 row_mask:0xf bank_mask:0xf bound_ctrl:1
	s_nop 1
	v_add_f32_dpp v142, v142, v142 row_ror:2 row_mask:0xf bank_mask:0xf bound_ctrl:1
	s_nop 1
	v_add_f32_dpp v142, v142, v142 row_ror:1 row_mask:0xf bank_mask:0xf bound_ctrl:1
	s_nop 0
	v_readlane_b32 s10, v142, 16
	v_readlane_b32 s11, v142, 48
	v_readlane_b32 s0, v142, 0
	v_readlane_b32 s1, v142, 32
	v_mov_b32_e32 v142, s10
	v_mov_b32_e32 v143, s11
	v_pk_add_f32 v[142:143], s[0:1], v[142:143]
	s_nop 0
	v_mov_b32_e32 v144, v142
	v_mov_b32_e32 v140, v143
	v_pk_add_f32 v[140:141], v[144:145], v[140:141]
	v_mov_b32_e32 v143, v175
	v_pk_fma_f32 v[140:141], v[140:141], s[6:7], v[90:91] op_sel_hi:[1,0,0]
	v_lshlrev_b32_e32 v143, 16, v143
	v_mul_f32_e32 v142, 0x4b800000, v141
	v_cmp_gt_f32_e64 s[12:13], s93, v141
	v_cmp_gt_f32_e64 s[10:11], s93, v140
	v_cndmask_b32_e32 v143, 0, v143, vcc
	v_cndmask_b32_e64 v141, v141, v142, s[12:13]
	v_rsq_f32_e32 v141, v141
	s_nop 0
	v_mul_f32_e32 v142, 0x45800000, v141
	v_cndmask_b32_e64 v141, v141, v142, s[12:13]
	v_mul_f32_e32 v141, v152, v141
	v_fma_f32 v141, v122, v141, v130
	v_fmac_f32_e32 v141, v146, v153
	v_mul_f32_e32 v141, v141, v154
	v_cvt_pk_bf16_f32 v146, v141, s0
	v_mul_f32_e32 v141, 0x4b800000, v140
	v_cndmask_b32_e64 v140, v140, v141, s[10:11]
	v_rsq_f32_e32 v140, v140
	v_mov_b32_e32 v142, v167
	v_mul_f32_e32 v141, 0x45800000, v140
	v_cndmask_b32_e64 v140, v140, v141, s[10:11]
	v_mov_b32_e32 v141, v159
	v_mul_f32_e32 v140, v155, v140
	v_fma_f32 v140, v123, v140, v131
	v_lshlrev_b32_e32 v142, 16, v142
	v_cndmask_b32_e64 v142, 0, v142, s[8:9]
	v_lshlrev_b32_e32 v141, 16, v141
	v_sub_f32_e32 v142, v142, v141
	v_sub_f32_e32 v143, v143, v141
	v_fmac_f32_e32 v141, v112, v142
	v_fmac_f32_e32 v141, v113, v143
	v_fmac_f32_e32 v140, v147, v141
	v_mov_b32_e32 v141, v207
	v_lshlrev_b32_e32 v141, 16, v141
	v_mul_f32_e32 v140, v140, v141
	v_cvt_pk_bf16_f32 v147, v140, s0
	v_mov_b32_e32 v140, v228
	s_waitcnt vmcnt(3)
	v_mov_b32_e32 v141, v235
	v_mov_b32_e32 v142, v160
	v_mov_b32_e32 v143, v193
	v_lshlrev_b32_e32 v140, 16, v140
	v_lshlrev_b32_e32 v141, 16, v141
	v_lshlrev_b32_e32 v153, 16, v142
	v_mov_b32_e32 v142, v168
	v_lshlrev_b32_e32 v143, 16, v143
	v_cndmask_b32_e32 v143, 0, v143, vcc
	v_sub_f32_e32 v143, v143, v153
	v_add_f32_e32 v152, v140, v141
	v_lshlrev_b32_e32 v142, 16, v142
	v_cndmask_b32_e64 v142, 0, v142, s[8:9]
	v_sub_f32_e32 v142, v142, v153
	v_fmac_f32_e32 v153, v114, v142
	v_mov_b32_e32 v142, v208
	v_fmac_f32_e32 v153, v115, v143
	v_add_f32_dpp v140, v152, v152 row_ror:8 row_mask:0xf bank_mask:0xf bound_ctrl:1
	v_lshlrev_b32_e32 v154, 16, v142
	v_mov_b32_e32 v142, v229
	s_waitcnt vmcnt(2)
; DEV float bf2f(bf16_t b) { return __uint_as_float(((unsigned)b) << 16); }
; DEV void phase_rw_post(const Params& p) {
;     ...
;     for (int h = 0; h < 8; ++h) {
;       const int hc = h * 64 + lane;
;       const float y = bf2f(raw[h][0]) + bf2f(raw[h][1]);
;       const float mu = wave_sum_dpp(y) * (1.f / 64.f);
;       const float dy = y - mu;
;       const float var = wave_sum_dpp(dy * dy) * (1.f / 64.f);
;       const float yn = dy * rsqrtf(var + 64e-5f) * p.in[26][hc] + p.in[27][hc];
;       const float x = bf2f(raw[h][2]);
;       const float v = x + p.in[14][1024 + hc] * ((hp ? bf2f(raw[h][3]) : 0.f) - x) + p.in[15][1024 + hc] * ((hn ? bf2f(raw[h][4]) : 0.f) - x);
;       res[h] = f2bf((yn + bo[h] * v) * bf2f(raw[h][5]));
	v_mov_b32_e32 v143, v236
	v_add_f32_dpp v140, v140, v140 row_ror:4 row_mask:0xf bank_mask:0xf bound_ctrl:1
	v_lshlrev_b32_e32 v142, 16, v142
	v_add_f32_dpp v140, v140, v140 row_ror:2 row_mask:0xf bank_mask:0xf bound_ctrl:1
	v_lshlrev_b32_e32 v143, 16, v143
	v_add_f32_e32 v155, v142, v143
	v_add_f32_dpp v140, v140, v140 row_ror:1 row_mask:0xf bank_mask:0xf bound_ctrl:1
	s_nop 0
	v_readlane_b32 s10, v140, 16
	v_readlane_b32 s11, v140, 48
	v_readlane_b32 s0, v140, 0
	v_readlane_b32 s1, v140, 32
	v_mov_b32_e32 v140, s10
	v_mov_b32_e32 v141, s11
	v_pk_add_f32 v[140:141], s[0:1], v[140:141]
	v_add_f32_dpp v142, v155, v155 row_ror:8 row_mask:0xf bank_mask:0xf bound_ctrl:1
	v_add_f32_e32 v140, v140, v141
	v_fmac_f32_e32 v152, 0xbc800000, v140
	v_mul_f32_e32 v140, v152, v152
	v_add_f32_dpp v142, v142, v142 row_ror:4 row_mask:0xf bank_mask:0xf bound_ctrl:1
	s_nop 0
	v_mov_b32_dpp v140, v140 row_ror:8 row_mask:0xf bank_mask:0xf bound_ctrl:1
	v_fmac_f32_e32 v140, v152, v152
	v_add_f32_dpp v142, v142, v142 row_ror:2 row_mask:0xf bank_mask:0xf bound_ctrl:1
	s_nop 0
	v_add_f32_dpp v140, v140, v140 row_ror:4 row_mask:0xf bank_mask:0xf bound_ctrl:1
	v_add_f32_dpp v142, v142, v142 row_ror:1 row_mask:0xf bank_mask:0xf bound_ctrl:1
	s_nop 0
	v_add_f32_dpp v140, v140, v140 row_ror:2 row_mask:0xf bank_mask:0xf bound_ctrl:1
	s_nop 1
	v_add_f32_dpp v140, v140, v140 row_ror:1 row_mask:0xf bank_mask:0xf bound_ctrl:1
	s_nop 0
	v_readlane_b32 s10, v140, 16
	v_readlane_b32 s11, v140, 48
	v_readlane_b32 s0, v140, 0
	v_readlane_b32 s1, v140, 32
	v_mov_b32_e32 v140, s10
	v_mov_b32_e32 v141, s11
	v_readlane_b32 s10, v142, 16
	v_readlane_b32 s11, v142, 48
	v_pk_add_f32 v[140:141], s[0:1], v[140:141]
	v_readlane_b32 s0, v142, 0
	v_readlane_b32 s1, v142, 32
	v_mov_b32_e32 v142, s10
	v_mov_b32_e32 v143, s11
	v_pk_add_f32 v[142:143], s[0:1], v[142:143]
	v_mov_b32_e32 v145, v140
	v_add_f32_e32 v142, v142, v143
	v_fmac_f32_e32 v155, 0xbc800000, v142
	v_mul_f32_e32 v142, v155, v155
	s_nop 1
	v_mov_b32_dpp v142, v142 row_ror:8 row_mask:0xf bank_mask:0xf bound_ctrl:1
	v_fmac_f32_e32 v142, v155, v155
	s_nop 1
	v_add_f32_dpp v142, v142, v142 row_ror:4 row_mask:0xf bank_mask:0xf bound_ctrl:1
	s_nop 1
	v_add_f32_dpp v142, v142, v142 row_ror:2 row_mask:0xf bank_mask:0xf bound_ctrl:1
	s_nop 1
	v_add_f32_dpp v142, v142, v142 row_ror:1 row_mask:0xf bank_mask:0xf bound_ctrl:1
	s_nop 0
	v_readlane_b32 s10, v142, 16
	v_readlane_b32 s11, v142, 48
	v_readlane_b32 s0, v142, 0
	v_readlane_b32 s1, v142, 32
	v_mov_b32_e32 v142, s10
	v_mov_b32_e32 v143, s11
	v_pk_add_f32 v[142:143], s[0:1], v[142:143]
	s_nop 0
	v_mov_b32_e32 v144, v142
	v_mov_b32_e32 v140, v143
	v_pk_add_f32 v[140:141], v[144:145], v[140:141]
	v_mov_b32_e32 v143, v195
	v_pk_fma_f32 v[140:141], v[140:141], s[6:7], v[90:91] op_sel_hi:[1,0,0]
	v_lshlrev_b32_e32 v143, 16, v143
	v_mul_f32_e32 v142, 0x4b800000, v141
	v_cmp_gt_f32_e64 s[12:13], s93, v141
	v_cmp_gt_f32_e64 s[10:11], s93, v140
	v_cndmask_b32_e32 v143, 0, v143, vcc
	v_cndmask_b32_e64 v141, v141, v142, s[12:13]
	v_rsq_f32_e32 v141, v141
	s_nop 0
	v_mul_f32_e32 v142, 0x45800000, v141
	v_cndmask_b32_e64 v141, v141, v142, s[12:13]
	v_mul_f32_e32 v141, v152, v141
	v_fma_f32 v141, v124, v141, v132
	v_fmac_f32_e32 v141, v148, v153
	v_mul_f32_e32 v141, v141, v154
	v_cvt_pk_bf16_f32 v144, v141, s0
	v_mul_f32_e32 v141, 0x4b800000, v140
	v_cndmask_b32_e64 v140, v140, v141, s[10:11]
	v_rsq_f32_e32 v140, v140
	v_mov_b32_e32 v142, v169
	v_mul_f32_e32 v141, 0x45800000, v140
	v_cndmask_b32_e64 v140, v140, v141, s[10:11]
	v_mov_b32_e32 v141, v161
	v_mul_f32_e32 v140, v155, v140
	v_fma_f32 v140, v125, v140, v133
	v_lshlrev_b32_e32 v142, 16, v142
	v_cndmask_b32_e64 v142, 0, v142, s[8:9]
	v_lshlrev_b32_e32 v141, 16, v141
	v_sub_f32_e32 v142, v142, v141
	v_sub_f32_e32 v143, v143, v141
	v_fmac_f32_e32 v141, v116, v142
	v_fmac_f32_e32 v141, v117, v143
	v_fmac_f32_e32 v140, v149, v141
	v_mov_b32_e32 v141, v209
	v_lshlrev_b32_e32 v141, 16, v141
	v_mul_f32_e32 v140, v140, v141
	v_cvt_pk_bf16_f32 v145, v140, s0
	v_mov_b32_e32 v140, v230
	s_waitcnt vmcnt(1)
	v_mov_b32_e32 v141, v237
	v_mov_b32_e32 v142, v162
	v_mov_b32_e32 v143, v196
	v_lshlrev_b32_e32 v140, 16, v140
	v_lshlrev_b32_e32 v141, 16, v141
	v_lshlrev_b32_e32 v149, 16, v142
	v_mov_b32_e32 v142, v170
	v_lshlrev_b32_e32 v143, 16, v143
	v_cndmask_b32_e32 v143, 0, v143, vcc
	v_sub_f32_e32 v143, v143, v149
	v_add_f32_e32 v148, v140, v141
	v_lshlrev_b32_e32 v142, 16, v142
	v_cndmask_b32_e64 v142, 0, v142, s[8:9]
	v_sub_f32_e32 v142, v142, v149
	v_fmac_f32_e32 v149, v118, v142
	v_mov_b32_e32 v142, v210
	s_nop 0
	v_mov_b32_e32 v86, v231
	s_nop 0
	s_waitcnt vmcnt(0)
; DEV float bf2f(bf16_t b) { return __uint_as_float(((unsigned)b) << 16); }
; DEV void phase_rw_post(const Params& p) {
;     ...
;     for (int h = 0; h < 8; ++h) {
;       const int hc = h * 64 + lane;
;       const float y = bf2f(raw[h][0]) + bf2f(raw[h][1]);
;       const float mu = wave_sum_dpp(y) * (1.f / 64.f);
;       const float dy = y - mu;
;       const float var = wave_sum_dpp(dy * dy) * (1.f / 64.f);
;       const float yn = dy * rsqrtf(var + 64e-5f) * p.in[26][hc] + p.in[27][hc];
;       const float x = bf2f(raw[h][2]);
;       const float v = x + p.in[14][1024 + hc] * ((hp ? bf2f(raw[h][3]) : 0.f) - x) + p.in[15][1024 + hc] * ((hn ? bf2f(raw[h][4]) : 0.f) - x);
;       res[h] = f2bf((yn + bo[h] * v) * bf2f(raw[h][5]));
;     }
; #pragma unroll
;     for (int h = 0; h < 8; ++h) yf[(size_t)t * 512 + h * 64 + lane] = res[h];
	v_mov_b32_e32 v87, v238
	v_add_f32_dpp v140, v148, v148 row_ror:8 row_mask:0xf bank_mask:0xf bound_ctrl:1
	v_mov_b32_e32 v80, v163
	v_fmac_f32_e32 v149, v119, v143
	v_mov_b32_e32 v81, v171
	v_add_f32_dpp v140, v140, v140 row_ror:4 row_mask:0xf bank_mask:0xf bound_ctrl:1
	v_mov_b32_e32 v82, v197
	v_lshlrev_b32_e32 v86, 16, v86
	v_add_f32_dpp v140, v140, v140 row_ror:2 row_mask:0xf bank_mask:0xf bound_ctrl:1
	v_lshlrev_b32_e32 v87, 16, v87
	v_add_f32_e32 v153, v86, v87
	v_add_f32_dpp v140, v140, v140 row_ror:1 row_mask:0xf bank_mask:0xf bound_ctrl:1
	v_lshlrev_b32_e32 v152, 16, v142
	v_readlane_b32 s10, v140, 16
	v_readlane_b32 s11, v140, 48
	v_readlane_b32 s0, v140, 0
	v_readlane_b32 s1, v140, 32
	v_mov_b32_e32 v140, s10
	v_mov_b32_e32 v141, s11
	v_pk_add_f32 v[140:141], s[0:1], v[140:141]
	v_add_f32_dpp v86, v153, v153 row_ror:8 row_mask:0xf bank_mask:0xf bound_ctrl:1
	v_add_f32_e32 v140, v140, v141
	v_fmac_f32_e32 v148, 0xbc800000, v140
	v_mul_f32_e32 v140, v148, v148
	v_add_f32_dpp v86, v86, v86 row_ror:4 row_mask:0xf bank_mask:0xf bound_ctrl:1
	v_lshlrev_b32_e32 v81, 16, v81
	v_mov_b32_dpp v140, v140 row_ror:8 row_mask:0xf bank_mask:0xf bound_ctrl:1
	v_fmac_f32_e32 v140, v148, v148
	v_add_f32_dpp v86, v86, v86 row_ror:2 row_mask:0xf bank_mask:0xf bound_ctrl:1
	v_lshlrev_b32_e32 v80, 16, v80
	v_add_f32_dpp v140, v140, v140 row_ror:4 row_mask:0xf bank_mask:0xf bound_ctrl:1
	v_add_f32_dpp v86, v86, v86 row_ror:1 row_mask:0xf bank_mask:0xf bound_ctrl:1
	v_cndmask_b32_e64 v81, 0, v81, s[8:9]
	v_add_f32_dpp v140, v140, v140 row_ror:2 row_mask:0xf bank_mask:0xf bound_ctrl:1
	v_lshlrev_b32_e32 v82, 16, v82
	v_sub_f32_e32 v81, v81, v80
	v_add_f32_dpp v140, v140, v140 row_ror:1 row_mask:0xf bank_mask:0xf bound_ctrl:1
	v_cndmask_b32_e32 v82, 0, v82, vcc
	v_readlane_b32 s10, v140, 16
	v_readlane_b32 s11, v140, 48
	v_readlane_b32 s0, v140, 0
	v_readlane_b32 s1, v140, 32
	v_mov_b32_e32 v140, s10
	v_mov_b32_e32 v141, s11
	v_readlane_b32 s10, v86, 16
	v_readlane_b32 s11, v86, 48
	v_pk_add_f32 v[140:141], s[0:1], v[140:141]
	v_readlane_b32 s0, v86, 0
	v_readlane_b32 s1, v86, 32
	v_mov_b32_e32 v86, s10
	v_mov_b32_e32 v87, s11
	v_pk_add_f32 v[86:87], s[0:1], v[86:87]
	v_mov_b32_e32 v143, v140
	v_add_f32_e32 v86, v86, v87
	v_fmac_f32_e32 v153, 0xbc800000, v86
	v_mul_f32_e32 v86, v153, v153
	v_sub_f32_e32 v82, v82, v80
	v_fmac_f32_e32 v80, v136, v81
	v_mov_b32_dpp v86, v86 row_ror:8 row_mask:0xf bank_mask:0xf bound_ctrl:1
	v_fmac_f32_e32 v86, v153, v153
	v_fmac_f32_e32 v80, v137, v82
	s_nop 0
	v_add_f32_dpp v86, v86, v86 row_ror:4 row_mask:0xf bank_mask:0xf bound_ctrl:1
	s_nop 1
	v_add_f32_dpp v86, v86, v86 row_ror:2 row_mask:0xf bank_mask:0xf bound_ctrl:1
	s_nop 1
	v_add_f32_dpp v86, v86, v86 row_ror:1 row_mask:0xf bank_mask:0xf bound_ctrl:1
	s_nop 0
	v_readlane_b32 s10, v86, 16
	v_readlane_b32 s11, v86, 48
	v_readlane_b32 s0, v86, 0
	v_readlane_b32 s1, v86, 32
	v_mov_b32_e32 v86, s10
	v_mov_b32_e32 v87, s11
	v_pk_add_f32 v[86:87], s[0:1], v[86:87]
	s_nop 0
	v_mov_b32_e32 v142, v86
	v_mov_b32_e32 v140, v87
	v_pk_add_f32 v[86:87], v[142:143], v[140:141]
	s_nop 0
	v_pk_fma_f32 v[86:87], v[86:87], s[6:7], v[90:91] op_sel_hi:[1,0,0]
	s_nop 0
	v_mul_f32_e32 v90, 0x4b800000, v87
	v_cmp_gt_f32_e64 s[12:13], s93, v87
	v_cmp_gt_f32_e64 s[10:11], s93, v86
	s_nop 0
	v_cndmask_b32_e64 v87, v87, v90, s[12:13]
	v_rsq_f32_e32 v87, v87
	s_nop 0
	v_mul_f32_e32 v90, 0x45800000, v87
	v_cndmask_b32_e64 v87, v87, v90, s[12:13]
	v_mul_f32_e32 v90, 0x4b800000, v86
	v_cndmask_b32_e64 v86, v86, v90, s[10:11]
	v_rsq_f32_e32 v86, v86
	v_mul_f32_e32 v87, v148, v87
	v_fma_f32 v87, v126, v87, v134
	v_fmac_f32_e32 v87, v139, v149
	v_mul_f32_e32 v90, 0x45800000, v86
	v_cndmask_b32_e64 v86, v86, v90, s[10:11]
	v_mul_f32_e32 v86, v153, v86
	v_fma_f32 v86, v127, v86, v135
	v_fmac_f32_e32 v86, v2, v80
	v_mov_b32_e32 v2, v211
	v_mul_f32_e32 v87, v87, v152
	v_cvt_pk_bf16_f32 v87, v87, s0
	v_lshlrev_b32_e32 v2, 16, v2
	v_mul_f32_e32 v2, v86, v2
	v_cvt_pk_bf16_f32 v2, v2, s0
	s_mov_b32 s0, 0xbfff
	v_cmp_lt_i32_e32 vcc, s0, v138
	s_or_b64 s[4:5], vcc, s[4:5]
	global_store_short v[78:79], v150, off
	global_store_short v[78:79], v151, off offset:128
	global_store_short v[78:79], v146, off offset:256
	global_store_short v[78:79], v147, off offset:384
	global_store_short v[78:79], v144, off offset:512
	global_store_short v[78:79], v145, off offset:640
	global_store_short v[78:79], v87, off offset:768
	global_store_short v[78:79], v2, off offset:896
	s_andn2_b64 exec, exec, s[4:5]
	s_cbranch_execnz .LBB0_2394
